# gate GEMM epilogue: all 16 attention-output loads issued up front into dead fragment registers, per-iteration vmcnt(15) (was 16 serial load->vmcnt(0)->store round trips)
# speedup vs baseline: 1.0045x; 1.0045x over previous
.LBB0_1077:
	s_lshl_b32 s0, s0, 8
	s_or_b32 s0, s0, s6
	s_ashr_i32 s56, s0, 6
	s_ashr_i32 s57, s56, 31
	v_lshl_add_u32 v150, s1, 8, v157
	v_or_b32_e32 v132, s0, v185
	v_bitop3_b32 v2, s0, 56, v185 bitop3:0xc8
	s_lshl_b64 s[0:1], s[56:57], 21
	v_ashrrev_i32_e32 v151, 31, v150
	s_add_u32 s54, s40, s0
	v_ashrrev_i32_e32 v133, 31, v132
	v_readlane_b32 s2, v253, 4
	v_lshlrev_b64 v[168:169], 7, v[150:151]
	s_addc_u32 s55, s41, s1
	v_lshlrev_b64 v[134:135], 11, v[150:151]
	v_readlane_b32 s3, v253, 5
	v_lshlrev_b64 v[152:153], 1, v[132:133]
	v_lshl_add_u64 v[132:133], s[54:55], 0, v[168:169]
	v_lshlrev_b32_e32 v2, 1, v2
	v_lshl_add_u64 v[134:135], s[2:3], 0, v[134:135]
	v_lshl_add_u64 v[132:133], v[132:133], 0, v[2:3]
	v_lshl_add_u64 v[154:155], v[134:135], 0, v[152:153]
	global_load_dwordx4 v[132:135], v[132:133], off
	v_mul_f32_e32 v151, 0xbfb8aa3b, v128
	v_exp_f32_e32 v151, v151
	s_or_b32 s0, s56, 2
	s_ashr_i32 s1, s0, 31
	s_lshl_b64 s[0:1], s[0:1], 21
	v_add_f32_e32 v151, 1.0, v151
	v_rcp_f32_e32 v176, v151
	v_mul_f32_e32 v151, 0xbfb8aa3b, v129
	v_exp_f32_e32 v151, v151
	s_add_u32 vcc_lo, s40, s0
	s_addc_u32 vcc_hi, s41, s1
	v_add_u32_e32 v248, v168, v2
	v_mov_b32_e32 v251, 0
	v_mov_b32_e32 v250, v248
	v_lshl_add_u64 v[186:187], vcc, 0, v[250:251]
	global_load_dwordx4 v[188:191], v[186:187], off
	v_add_u32_e32 v250, 0x800, v248
	v_lshl_add_u64 v[186:187], s[54:55], 0, v[250:251]
	global_load_dwordx4 v[192:195], v[186:187], off
	v_add_u32_e32 v250, 0x800, v248
	v_lshl_add_u64 v[186:187], vcc, 0, v[250:251]
	global_load_dwordx4 v[196:199], v[186:187], off
	v_add_u32_e32 v250, 0x1000, v248
	v_lshl_add_u64 v[186:187], s[54:55], 0, v[250:251]
	global_load_dwordx4 v[200:203], v[186:187], off
	v_add_u32_e32 v250, 0x1000, v248
	v_lshl_add_u64 v[186:187], vcc, 0, v[250:251]
	global_load_dwordx4 v[204:207], v[186:187], off
	v_add_u32_e32 v250, 0x1800, v248
	v_lshl_add_u64 v[186:187], s[54:55], 0, v[250:251]
	global_load_dwordx4 v[208:211], v[186:187], off
	v_add_u32_e32 v250, 0x1800, v248
	v_lshl_add_u64 v[186:187], vcc, 0, v[250:251]
	global_load_dwordx4 v[212:215], v[186:187], off
	v_add_u32_e32 v250, 0x4000, v248
	v_lshl_add_u64 v[186:187], s[54:55], 0, v[250:251]
	global_load_dwordx4 v[216:219], v[186:187], off
	v_add_u32_e32 v250, 0x4000, v248
	v_lshl_add_u64 v[186:187], vcc, 0, v[250:251]
	global_load_dwordx4 v[220:223], v[186:187], off
	v_add_u32_e32 v250, 0x4800, v248
	v_lshl_add_u64 v[186:187], s[54:55], 0, v[250:251]
	global_load_dwordx4 v[224:227], v[186:187], off
	v_add_u32_e32 v250, 0x4800, v248
	v_lshl_add_u64 v[186:187], vcc, 0, v[250:251]
	global_load_dwordx4 v[228:231], v[186:187], off
	v_add_u32_e32 v250, 0x5000, v248
	v_lshl_add_u64 v[186:187], s[54:55], 0, v[250:251]
	global_load_dwordx4 v[232:235], v[186:187], off
	v_add_u32_e32 v250, 0x5000, v248
	v_lshl_add_u64 v[186:187], vcc, 0, v[250:251]
	global_load_dwordx4 v[236:239], v[186:187], off
	v_add_u32_e32 v250, 0x5800, v248
	v_lshl_add_u64 v[186:187], s[54:55], 0, v[250:251]
	global_load_dwordx4 v[240:243], v[186:187], off
	v_add_u32_e32 v250, 0x5800, v248
	v_lshl_add_u64 v[186:187], vcc, 0, v[250:251]
	global_load_dwordx4 v[244:247], v[186:187], off
	v_add_f32_e32 v151, 1.0, v151
	v_rcp_f32_e32 v177, v151
	s_waitcnt vmcnt(15)
	v_lshlrev_b32_e32 v178, 16, v132
	v_and_b32_e32 v179, 0xffff0000, v132
	v_pk_mul_f32 v[128:129], v[128:129], v[176:177]
	v_lshlrev_b32_e32 v132, 16, v133
	v_pk_mul_f32 v[128:129], v[128:129], v[178:179]
	v_and_b32_e32 v133, 0xffff0000, v133
	v_cvt_pk_bf16_f32 v128, v128, v129
	v_mul_f32_e32 v129, 0xbfb8aa3b, v130
	v_exp_f32_e32 v129, v129
	s_nop 0
	v_add_f32_e32 v129, 1.0, v129
	v_rcp_f32_e32 v176, v129
	v_mul_f32_e32 v129, 0xbfb8aa3b, v131
	v_exp_f32_e32 v129, v129
	s_nop 0
	v_add_f32_e32 v129, 1.0, v129
	v_rcp_f32_e32 v177, v129
	s_nop 0
	v_pk_mul_f32 v[130:131], v[130:131], v[176:177]
	s_nop 0
	v_pk_mul_f32 v[130:131], v[130:131], v[132:133]
	v_lshlrev_b32_e32 v132, 16, v134
	v_cvt_pk_bf16_f32 v129, v130, v131
	v_mul_f32_e32 v130, 0xbfb8aa3b, v124
	v_mul_f32_e32 v131, 0xbfb8aa3b, v125
	v_exp_f32_e32 v130, v130
	v_exp_f32_e32 v131, v131
	v_and_b32_e32 v133, 0xffff0000, v134
	v_add_f32_e32 v130, 1.0, v130
	v_add_f32_e32 v131, 1.0, v131
	v_rcp_f32_e32 v130, v130
	v_rcp_f32_e32 v131, v131
	s_nop 0
	v_pk_mul_f32 v[124:125], v[124:125], v[130:131]
	s_nop 0
	v_pk_mul_f32 v[124:125], v[124:125], v[132:133]
	v_lshlrev_b32_e32 v132, 16, v135
	v_cvt_pk_bf16_f32 v130, v124, v125
	v_mul_f32_e32 v124, 0xbfb8aa3b, v126
	v_mul_f32_e32 v125, 0xbfb8aa3b, v127
	v_exp_f32_e32 v124, v124
	v_exp_f32_e32 v125, v125
	v_and_b32_e32 v133, 0xffff0000, v135
	v_add_f32_e32 v124, 1.0, v124
	v_add_f32_e32 v125, 1.0, v125
	v_rcp_f32_e32 v124, v124
	v_rcp_f32_e32 v125, v125
	s_nop 0
	v_pk_mul_f32 v[124:125], v[126:127], v[124:125]
	s_nop 0
	v_pk_mul_f32 v[124:125], v[124:125], v[132:133]
	s_nop 0
	v_cvt_pk_bf16_f32 v131, v124, v125
	v_lshl_add_u64 v[124:125], vcc, 0, v[168:169]
	global_store_dwordx4 v[154:155], v[128:131], off
	v_lshl_add_u64 v[124:125], v[124:125], 0, v[2:3]
	s_nop 1
	v_mul_f32_e32 v128, 0xbfb8aa3b, v120
	v_mul_f32_e32 v129, 0xbfb8aa3b, v121
	v_exp_f32_e32 v128, v128
	v_exp_f32_e32 v129, v129
	v_add_f32_e32 v128, 1.0, v128
	v_add_f32_e32 v129, 1.0, v129
	v_rcp_f32_e32 v128, v128
	v_rcp_f32_e32 v129, v129
	s_waitcnt vmcnt(15)
	v_mov_b32_e32 v124, v188
	v_mov_b32_e32 v125, v189
	v_mov_b32_e32 v126, v190
	v_mov_b32_e32 v127, v191
	v_lshlrev_b32_e32 v130, 16, v124
	v_and_b32_e32 v131, 0xffff0000, v124
	v_pk_mul_f32 v[120:121], v[120:121], v[128:129]
	v_lshlrev_b32_e32 v124, 16, v125
	v_pk_mul_f32 v[120:121], v[120:121], v[130:131]
	v_and_b32_e32 v125, 0xffff0000, v125
	v_cvt_pk_bf16_f32 v120, v120, v121
	v_mul_f32_e32 v121, 0xbfb8aa3b, v122
	v_exp_f32_e32 v121, v121
	s_nop 0
	v_add_f32_e32 v121, 1.0, v121
	v_rcp_f32_e32 v128, v121
	v_mul_f32_e32 v121, 0xbfb8aa3b, v123
	v_exp_f32_e32 v121, v121
	s_nop 0
	v_add_f32_e32 v121, 1.0, v121
	v_rcp_f32_e32 v129, v121
	s_nop 0
	v_pk_mul_f32 v[122:123], v[122:123], v[128:129]
	s_nop 0
	v_pk_mul_f32 v[122:123], v[122:123], v[124:125]
	v_lshlrev_b32_e32 v124, 16, v126
	v_cvt_pk_bf16_f32 v121, v122, v123
	v_mul_f32_e32 v122, 0xbfb8aa3b, v116
	v_mul_f32_e32 v123, 0xbfb8aa3b, v117
	v_exp_f32_e32 v122, v122
	v_exp_f32_e32 v123, v123
	v_and_b32_e32 v125, 0xffff0000, v126
	v_add_f32_e32 v122, 1.0, v122
	v_add_f32_e32 v123, 1.0, v123
	v_rcp_f32_e32 v122, v122
	v_rcp_f32_e32 v123, v123
	s_nop 0
	v_pk_mul_f32 v[116:117], v[116:117], v[122:123]
	s_nop 0
	v_pk_mul_f32 v[116:117], v[116:117], v[124:125]
	v_lshlrev_b32_e32 v124, 16, v127
	v_cvt_pk_bf16_f32 v122, v116, v117
	v_mul_f32_e32 v116, 0xbfb8aa3b, v118
	v_mul_f32_e32 v117, 0xbfb8aa3b, v119
	v_exp_f32_e32 v116, v116
	v_exp_f32_e32 v117, v117
	v_and_b32_e32 v125, 0xffff0000, v127
	v_add_f32_e32 v116, 1.0, v116
	v_add_f32_e32 v117, 1.0, v117
	v_rcp_f32_e32 v116, v116
	v_rcp_f32_e32 v117, v117
	s_nop 0
	v_pk_mul_f32 v[116:117], v[118:119], v[116:117]
	v_or_b32_e32 v118, 16, v150
	v_pk_mul_f32 v[116:117], v[116:117], v[124:125]
	v_ashrrev_i32_e32 v119, 31, v118
	v_cvt_pk_bf16_f32 v123, v116, v117
	v_lshlrev_b64 v[116:117], 11, v[118:119]
	v_lshlrev_b64 v[118:119], 7, v[118:119]
	global_store_dwordx4 v[154:155], v[120:123], off offset:256
	v_mul_f32_e32 v124, 0xbfb8aa3b, v112
	v_mul_f32_e32 v125, 0xbfb8aa3b, v113
	v_lshl_add_u64 v[120:121], s[54:55], 0, v[118:119]
	v_lshl_add_u64 v[120:121], v[120:121], 0, v[2:3]
	s_nop 1
	v_exp_f32_e32 v124, v124
	v_exp_f32_e32 v125, v125
	v_lshl_add_u64 v[116:117], s[2:3], 0, v[116:117]
	v_lshl_add_u64 v[116:117], v[116:117], 0, v[152:153]
	v_add_f32_e32 v124, 1.0, v124
	v_add_f32_e32 v125, 1.0, v125
	v_rcp_f32_e32 v124, v124
	v_rcp_f32_e32 v125, v125
	s_waitcnt vmcnt(15)
	v_mov_b32_e32 v120, v192
	v_mov_b32_e32 v121, v193
	v_mov_b32_e32 v122, v194
	v_mov_b32_e32 v123, v195
	v_lshlrev_b32_e32 v126, 16, v120
	v_and_b32_e32 v127, 0xffff0000, v120
	v_pk_mul_f32 v[112:113], v[112:113], v[124:125]
	v_lshlrev_b32_e32 v120, 16, v121
	v_pk_mul_f32 v[112:113], v[112:113], v[126:127]
	v_and_b32_e32 v121, 0xffff0000, v121
	v_cvt_pk_bf16_f32 v112, v112, v113
	v_mul_f32_e32 v113, 0xbfb8aa3b, v114
	v_exp_f32_e32 v113, v113
	s_nop 0
	v_add_f32_e32 v113, 1.0, v113
	v_rcp_f32_e32 v124, v113
	v_mul_f32_e32 v113, 0xbfb8aa3b, v115
	v_exp_f32_e32 v113, v113
	s_nop 0
	v_add_f32_e32 v113, 1.0, v113
	v_rcp_f32_e32 v125, v113
	s_nop 0
	v_pk_mul_f32 v[114:115], v[114:115], v[124:125]
	s_nop 0
	v_pk_mul_f32 v[114:115], v[114:115], v[120:121]
	v_lshlrev_b32_e32 v120, 16, v122
	v_cvt_pk_bf16_f32 v113, v114, v115
	v_mul_f32_e32 v114, 0xbfb8aa3b, v108
	v_mul_f32_e32 v115, 0xbfb8aa3b, v109
	v_exp_f32_e32 v114, v114
	v_exp_f32_e32 v115, v115
	v_and_b32_e32 v121, 0xffff0000, v122
	v_add_f32_e32 v114, 1.0, v114
	v_add_f32_e32 v115, 1.0, v115
	v_rcp_f32_e32 v114, v114
	v_rcp_f32_e32 v115, v115
	s_nop 0
	v_pk_mul_f32 v[108:109], v[108:109], v[114:115]
	s_nop 0
	v_pk_mul_f32 v[108:109], v[108:109], v[120:121]
	v_lshlrev_b32_e32 v120, 16, v123
	v_cvt_pk_bf16_f32 v114, v108, v109
	v_mul_f32_e32 v108, 0xbfb8aa3b, v110
	v_mul_f32_e32 v109, 0xbfb8aa3b, v111
	v_exp_f32_e32 v108, v108
	v_exp_f32_e32 v109, v109
	v_and_b32_e32 v121, 0xffff0000, v123
	v_add_f32_e32 v108, 1.0, v108
	v_add_f32_e32 v109, 1.0, v109
	v_rcp_f32_e32 v108, v108
	v_rcp_f32_e32 v109, v109
	s_nop 0
	v_pk_mul_f32 v[108:109], v[110:111], v[108:109]
	s_nop 0
	v_pk_mul_f32 v[108:109], v[108:109], v[120:121]
	s_nop 0
	v_cvt_pk_bf16_f32 v115, v108, v109
	v_lshl_add_u64 v[108:109], vcc, 0, v[118:119]
	global_store_dwordx4 v[116:117], v[112:115], off
	v_lshl_add_u64 v[108:109], v[108:109], 0, v[2:3]
	s_nop 1
	v_mul_f32_e32 v112, 0xbfb8aa3b, v104
	v_mul_f32_e32 v113, 0xbfb8aa3b, v105
	v_exp_f32_e32 v112, v112
	v_exp_f32_e32 v113, v113
	v_add_f32_e32 v112, 1.0, v112
	v_add_f32_e32 v113, 1.0, v113
	v_rcp_f32_e32 v112, v112
	v_rcp_f32_e32 v113, v113
	s_waitcnt vmcnt(15)
	v_mov_b32_e32 v108, v196
	v_mov_b32_e32 v109, v197
	v_mov_b32_e32 v110, v198
	v_mov_b32_e32 v111, v199
	v_lshlrev_b32_e32 v114, 16, v108
	v_and_b32_e32 v115, 0xffff0000, v108
	v_pk_mul_f32 v[104:105], v[104:105], v[112:113]
	v_lshlrev_b32_e32 v108, 16, v109
	v_pk_mul_f32 v[104:105], v[104:105], v[114:115]
	v_and_b32_e32 v109, 0xffff0000, v109
	v_cvt_pk_bf16_f32 v104, v104, v105
	v_mul_f32_e32 v105, 0xbfb8aa3b, v106
	v_exp_f32_e32 v105, v105
	s_nop 0
	v_add_f32_e32 v105, 1.0, v105
	v_rcp_f32_e32 v112, v105
	v_mul_f32_e32 v105, 0xbfb8aa3b, v107
	v_exp_f32_e32 v105, v105
	s_nop 0
	v_add_f32_e32 v105, 1.0, v105
	v_rcp_f32_e32 v113, v105
	s_nop 0
	v_pk_mul_f32 v[106:107], v[106:107], v[112:113]
	s_nop 0
	v_pk_mul_f32 v[106:107], v[106:107], v[108:109]
	v_lshlrev_b32_e32 v108, 16, v110
	v_cvt_pk_bf16_f32 v105, v106, v107
	v_mul_f32_e32 v106, 0xbfb8aa3b, v100
	v_mul_f32_e32 v107, 0xbfb8aa3b, v101
	v_exp_f32_e32 v106, v106
	v_exp_f32_e32 v107, v107
	v_and_b32_e32 v109, 0xffff0000, v110
	v_add_f32_e32 v106, 1.0, v106
	v_add_f32_e32 v107, 1.0, v107
	v_rcp_f32_e32 v106, v106
	v_rcp_f32_e32 v107, v107
	s_nop 0
	v_pk_mul_f32 v[100:101], v[100:101], v[106:107]
	s_nop 0
	v_pk_mul_f32 v[100:101], v[100:101], v[108:109]
	v_lshlrev_b32_e32 v108, 16, v111
	v_cvt_pk_bf16_f32 v106, v100, v101
	v_mul_f32_e32 v100, 0xbfb8aa3b, v102
	v_mul_f32_e32 v101, 0xbfb8aa3b, v103
	v_exp_f32_e32 v100, v100
	v_exp_f32_e32 v101, v101
	v_and_b32_e32 v109, 0xffff0000, v111
	v_add_f32_e32 v100, 1.0, v100
	v_add_f32_e32 v101, 1.0, v101
	v_rcp_f32_e32 v100, v100
	v_rcp_f32_e32 v101, v101
	s_nop 0
	v_pk_mul_f32 v[100:101], v[102:103], v[100:101]
	v_or_b32_e32 v102, 32, v150
	v_pk_mul_f32 v[100:101], v[100:101], v[108:109]
	v_ashrrev_i32_e32 v103, 31, v102
	v_cvt_pk_bf16_f32 v107, v100, v101
	v_lshlrev_b64 v[100:101], 11, v[102:103]
	v_lshlrev_b64 v[102:103], 7, v[102:103]
	global_store_dwordx4 v[116:117], v[104:107], off offset:256
	v_mul_f32_e32 v108, 0xbfb8aa3b, v96
	v_mul_f32_e32 v109, 0xbfb8aa3b, v97
	v_lshl_add_u64 v[104:105], s[54:55], 0, v[102:103]
	v_lshl_add_u64 v[104:105], v[104:105], 0, v[2:3]
	s_nop 1
	v_exp_f32_e32 v108, v108
	v_exp_f32_e32 v109, v109
	v_lshl_add_u64 v[100:101], s[2:3], 0, v[100:101]
	v_lshl_add_u64 v[100:101], v[100:101], 0, v[152:153]
	v_add_f32_e32 v108, 1.0, v108
	v_add_f32_e32 v109, 1.0, v109
	v_rcp_f32_e32 v108, v108
	v_rcp_f32_e32 v109, v109
	s_waitcnt vmcnt(15)
	v_mov_b32_e32 v104, v200
	v_mov_b32_e32 v105, v201
	v_mov_b32_e32 v106, v202
	v_mov_b32_e32 v107, v203
	v_lshlrev_b32_e32 v110, 16, v104
	v_and_b32_e32 v111, 0xffff0000, v104
	v_pk_mul_f32 v[96:97], v[96:97], v[108:109]
	v_lshlrev_b32_e32 v104, 16, v105
	v_pk_mul_f32 v[96:97], v[96:97], v[110:111]
	v_and_b32_e32 v105, 0xffff0000, v105
	v_cvt_pk_bf16_f32 v96, v96, v97
	v_mul_f32_e32 v97, 0xbfb8aa3b, v98
	v_exp_f32_e32 v97, v97
	s_nop 0
	v_add_f32_e32 v97, 1.0, v97
	v_rcp_f32_e32 v108, v97
	v_mul_f32_e32 v97, 0xbfb8aa3b, v99
	v_exp_f32_e32 v97, v97
	s_nop 0
	v_add_f32_e32 v97, 1.0, v97
	v_rcp_f32_e32 v109, v97
	s_nop 0
	v_pk_mul_f32 v[98:99], v[98:99], v[108:109]
	s_nop 0
	v_pk_mul_f32 v[98:99], v[98:99], v[104:105]
	v_lshlrev_b32_e32 v104, 16, v106
	v_cvt_pk_bf16_f32 v97, v98, v99
	v_mul_f32_e32 v98, 0xbfb8aa3b, v92
	v_mul_f32_e32 v99, 0xbfb8aa3b, v93
	v_exp_f32_e32 v98, v98
	v_exp_f32_e32 v99, v99
	v_and_b32_e32 v105, 0xffff0000, v106
	v_add_f32_e32 v98, 1.0, v98
	v_add_f32_e32 v99, 1.0, v99
	v_rcp_f32_e32 v98, v98
	v_rcp_f32_e32 v99, v99
	s_nop 0
	v_pk_mul_f32 v[92:93], v[92:93], v[98:99]
	s_nop 0
	v_pk_mul_f32 v[92:93], v[92:93], v[104:105]
	v_lshlrev_b32_e32 v104, 16, v107
	v_cvt_pk_bf16_f32 v98, v92, v93
	v_mul_f32_e32 v92, 0xbfb8aa3b, v94
	v_mul_f32_e32 v93, 0xbfb8aa3b, v95
	v_exp_f32_e32 v92, v92
	v_exp_f32_e32 v93, v93
	v_and_b32_e32 v105, 0xffff0000, v107
	v_add_f32_e32 v92, 1.0, v92
	v_add_f32_e32 v93, 1.0, v93
	v_rcp_f32_e32 v92, v92
	v_rcp_f32_e32 v93, v93
	s_nop 0
	v_pk_mul_f32 v[92:93], v[94:95], v[92:93]
	s_nop 0
	v_pk_mul_f32 v[92:93], v[92:93], v[104:105]
	s_nop 0
	v_cvt_pk_bf16_f32 v99, v92, v93
	v_lshl_add_u64 v[92:93], vcc, 0, v[102:103]
	global_store_dwordx4 v[100:101], v[96:99], off
	v_lshl_add_u64 v[92:93], v[92:93], 0, v[2:3]
	s_nop 1
	v_mul_f32_e32 v96, 0xbfb8aa3b, v88
	v_mul_f32_e32 v97, 0xbfb8aa3b, v89
	v_exp_f32_e32 v96, v96
	v_exp_f32_e32 v97, v97
	v_add_f32_e32 v96, 1.0, v96
	v_add_f32_e32 v97, 1.0, v97
	v_rcp_f32_e32 v96, v96
	v_rcp_f32_e32 v97, v97
	s_waitcnt vmcnt(15)
	v_mov_b32_e32 v92, v204
	v_mov_b32_e32 v93, v205
	v_mov_b32_e32 v94, v206
	v_mov_b32_e32 v95, v207
	v_lshlrev_b32_e32 v98, 16, v92
	v_and_b32_e32 v99, 0xffff0000, v92
	v_pk_mul_f32 v[88:89], v[88:89], v[96:97]
	v_lshlrev_b32_e32 v92, 16, v93
	v_pk_mul_f32 v[88:89], v[88:89], v[98:99]
	v_and_b32_e32 v93, 0xffff0000, v93
	v_cvt_pk_bf16_f32 v88, v88, v89
	v_mul_f32_e32 v89, 0xbfb8aa3b, v90
	v_exp_f32_e32 v89, v89
	s_nop 0
	v_add_f32_e32 v89, 1.0, v89
	v_rcp_f32_e32 v96, v89
	v_mul_f32_e32 v89, 0xbfb8aa3b, v91
	v_exp_f32_e32 v89, v89
	s_nop 0
	v_add_f32_e32 v89, 1.0, v89
	v_rcp_f32_e32 v97, v89
	s_nop 0
	v_pk_mul_f32 v[90:91], v[90:91], v[96:97]
	s_nop 0
	v_pk_mul_f32 v[90:91], v[90:91], v[92:93]
	v_lshlrev_b32_e32 v92, 16, v94
	v_cvt_pk_bf16_f32 v89, v90, v91
	v_mul_f32_e32 v90, 0xbfb8aa3b, v84
	v_mul_f32_e32 v91, 0xbfb8aa3b, v85
	v_exp_f32_e32 v90, v90
	v_exp_f32_e32 v91, v91
	v_and_b32_e32 v93, 0xffff0000, v94
	v_add_f32_e32 v90, 1.0, v90
	v_add_f32_e32 v91, 1.0, v91
	v_rcp_f32_e32 v90, v90
	v_rcp_f32_e32 v91, v91
	s_nop 0
	v_pk_mul_f32 v[84:85], v[84:85], v[90:91]
	s_nop 0
	v_pk_mul_f32 v[84:85], v[84:85], v[92:93]
	v_lshlrev_b32_e32 v92, 16, v95
	v_cvt_pk_bf16_f32 v90, v84, v85
	v_mul_f32_e32 v84, 0xbfb8aa3b, v86
	v_mul_f32_e32 v85, 0xbfb8aa3b, v87
	v_exp_f32_e32 v84, v84
	v_exp_f32_e32 v85, v85
	v_and_b32_e32 v93, 0xffff0000, v95
	v_add_f32_e32 v84, 1.0, v84
	v_add_f32_e32 v85, 1.0, v85
	v_rcp_f32_e32 v84, v84
	v_rcp_f32_e32 v85, v85
	s_nop 0
	v_pk_mul_f32 v[84:85], v[86:87], v[84:85]
	v_or_b32_e32 v86, 48, v150
	v_pk_mul_f32 v[84:85], v[84:85], v[92:93]
	v_ashrrev_i32_e32 v87, 31, v86
	v_cvt_pk_bf16_f32 v91, v84, v85
	v_lshlrev_b64 v[84:85], 11, v[86:87]
	v_lshlrev_b64 v[86:87], 7, v[86:87]
	global_store_dwordx4 v[100:101], v[88:91], off offset:256
	v_mul_f32_e32 v92, 0xbfb8aa3b, v80
	v_mul_f32_e32 v93, 0xbfb8aa3b, v81
	v_lshl_add_u64 v[88:89], s[54:55], 0, v[86:87]
	v_lshl_add_u64 v[88:89], v[88:89], 0, v[2:3]
	s_nop 1
	v_exp_f32_e32 v92, v92
	v_exp_f32_e32 v93, v93
	v_lshl_add_u64 v[84:85], s[2:3], 0, v[84:85]
	v_lshl_add_u64 v[84:85], v[84:85], 0, v[152:153]
	v_add_f32_e32 v92, 1.0, v92
	v_add_f32_e32 v93, 1.0, v93
	v_rcp_f32_e32 v92, v92
	v_rcp_f32_e32 v93, v93
	s_waitcnt vmcnt(15)
	v_mov_b32_e32 v88, v208
	v_mov_b32_e32 v89, v209
	v_mov_b32_e32 v90, v210
	v_mov_b32_e32 v91, v211
	v_lshlrev_b32_e32 v94, 16, v88
	v_and_b32_e32 v95, 0xffff0000, v88
	v_pk_mul_f32 v[80:81], v[80:81], v[92:93]
	v_lshlrev_b32_e32 v88, 16, v89
	v_pk_mul_f32 v[80:81], v[80:81], v[94:95]
	v_and_b32_e32 v89, 0xffff0000, v89
	v_cvt_pk_bf16_f32 v80, v80, v81
	v_mul_f32_e32 v81, 0xbfb8aa3b, v82
	v_exp_f32_e32 v81, v81
	s_nop 0
	v_add_f32_e32 v81, 1.0, v81
	v_rcp_f32_e32 v92, v81
	v_mul_f32_e32 v81, 0xbfb8aa3b, v83
	v_exp_f32_e32 v81, v81
	s_nop 0
	v_add_f32_e32 v81, 1.0, v81
	v_rcp_f32_e32 v93, v81
	s_nop 0
	v_pk_mul_f32 v[82:83], v[82:83], v[92:93]
	s_nop 0
	v_pk_mul_f32 v[82:83], v[82:83], v[88:89]
	v_lshlrev_b32_e32 v88, 16, v90
	v_cvt_pk_bf16_f32 v81, v82, v83
	v_mul_f32_e32 v82, 0xbfb8aa3b, v76
	v_mul_f32_e32 v83, 0xbfb8aa3b, v77
	v_exp_f32_e32 v82, v82
	v_exp_f32_e32 v83, v83
	v_and_b32_e32 v89, 0xffff0000, v90
	v_add_f32_e32 v82, 1.0, v82
	v_add_f32_e32 v83, 1.0, v83
	v_rcp_f32_e32 v82, v82
	v_rcp_f32_e32 v83, v83
	s_nop 0
	v_pk_mul_f32 v[76:77], v[76:77], v[82:83]
	s_nop 0
	v_pk_mul_f32 v[76:77], v[76:77], v[88:89]
	v_lshlrev_b32_e32 v88, 16, v91
	v_cvt_pk_bf16_f32 v82, v76, v77
	v_mul_f32_e32 v76, 0xbfb8aa3b, v78
	v_mul_f32_e32 v77, 0xbfb8aa3b, v79
	v_exp_f32_e32 v76, v76
	v_exp_f32_e32 v77, v77
	v_and_b32_e32 v89, 0xffff0000, v91
	v_add_f32_e32 v76, 1.0, v76
	v_add_f32_e32 v77, 1.0, v77
	v_rcp_f32_e32 v76, v76
	v_rcp_f32_e32 v77, v77
	s_nop 0
	v_pk_mul_f32 v[76:77], v[78:79], v[76:77]
	s_nop 0
	v_pk_mul_f32 v[76:77], v[76:77], v[88:89]
	s_nop 0
	v_cvt_pk_bf16_f32 v83, v76, v77
	v_lshl_add_u64 v[76:77], vcc, 0, v[86:87]
	global_store_dwordx4 v[84:85], v[80:83], off
	v_lshl_add_u64 v[76:77], v[76:77], 0, v[2:3]
	s_nop 1
	v_mul_f32_e32 v80, 0xbfb8aa3b, v72
	v_mul_f32_e32 v81, 0xbfb8aa3b, v73
	v_exp_f32_e32 v80, v80
	v_exp_f32_e32 v81, v81
	v_add_f32_e32 v80, 1.0, v80
	v_add_f32_e32 v81, 1.0, v81
	v_rcp_f32_e32 v80, v80
	v_rcp_f32_e32 v81, v81
	s_waitcnt vmcnt(15)
	v_mov_b32_e32 v76, v212
	v_mov_b32_e32 v77, v213
	v_mov_b32_e32 v78, v214
	v_mov_b32_e32 v79, v215
	v_lshlrev_b32_e32 v82, 16, v76
	v_and_b32_e32 v83, 0xffff0000, v76
	v_pk_mul_f32 v[72:73], v[72:73], v[80:81]
	v_lshlrev_b32_e32 v76, 16, v77
	v_pk_mul_f32 v[72:73], v[72:73], v[82:83]
	v_and_b32_e32 v77, 0xffff0000, v77
	v_cvt_pk_bf16_f32 v72, v72, v73
	v_mul_f32_e32 v73, 0xbfb8aa3b, v74
	v_exp_f32_e32 v73, v73
	s_nop 0
	v_add_f32_e32 v73, 1.0, v73
	v_rcp_f32_e32 v80, v73
	v_mul_f32_e32 v73, 0xbfb8aa3b, v75
	v_exp_f32_e32 v73, v73
	s_nop 0
	v_add_f32_e32 v73, 1.0, v73
	v_rcp_f32_e32 v81, v73
	s_nop 0
	v_pk_mul_f32 v[74:75], v[74:75], v[80:81]
	s_nop 0
	v_pk_mul_f32 v[74:75], v[74:75], v[76:77]
	v_lshlrev_b32_e32 v76, 16, v78
	v_cvt_pk_bf16_f32 v73, v74, v75
	v_mul_f32_e32 v74, 0xbfb8aa3b, v68
	v_mul_f32_e32 v75, 0xbfb8aa3b, v69
	v_exp_f32_e32 v74, v74
	v_exp_f32_e32 v75, v75
	v_and_b32_e32 v77, 0xffff0000, v78
	v_add_f32_e32 v74, 1.0, v74
	v_add_f32_e32 v75, 1.0, v75
	v_rcp_f32_e32 v74, v74
	v_rcp_f32_e32 v75, v75
	s_nop 0
	v_pk_mul_f32 v[68:69], v[68:69], v[74:75]
	s_nop 0
	v_pk_mul_f32 v[68:69], v[68:69], v[76:77]
	v_lshlrev_b32_e32 v76, 16, v79
	v_cvt_pk_bf16_f32 v74, v68, v69
	v_mul_f32_e32 v68, 0xbfb8aa3b, v70
	v_mul_f32_e32 v69, 0xbfb8aa3b, v71
	v_exp_f32_e32 v68, v68
	v_exp_f32_e32 v69, v69
	v_and_b32_e32 v77, 0xffff0000, v79
	v_add_f32_e32 v68, 1.0, v68
	v_add_f32_e32 v69, 1.0, v69
	v_rcp_f32_e32 v68, v68
	v_rcp_f32_e32 v69, v69
	s_nop 0
	v_pk_mul_f32 v[68:69], v[70:71], v[68:69]
	v_add_u32_e32 v70, 0x80, v150
	v_pk_mul_f32 v[68:69], v[68:69], v[76:77]
	v_ashrrev_i32_e32 v71, 31, v70
	v_cvt_pk_bf16_f32 v75, v68, v69
	v_lshlrev_b64 v[68:69], 11, v[70:71]
	v_lshlrev_b64 v[70:71], 7, v[70:71]
	global_store_dwordx4 v[84:85], v[72:75], off offset:256
	v_mul_f32_e32 v76, 0xbfb8aa3b, v64
	v_mul_f32_e32 v77, 0xbfb8aa3b, v65
	v_lshl_add_u64 v[72:73], s[54:55], 0, v[70:71]
	v_lshl_add_u64 v[72:73], v[72:73], 0, v[2:3]
	s_nop 1
	v_exp_f32_e32 v76, v76
	v_exp_f32_e32 v77, v77
	v_lshl_add_u64 v[68:69], s[2:3], 0, v[68:69]
	v_lshl_add_u64 v[68:69], v[68:69], 0, v[152:153]
	v_add_f32_e32 v76, 1.0, v76
	v_add_f32_e32 v77, 1.0, v77
	v_rcp_f32_e32 v76, v76
	v_rcp_f32_e32 v77, v77
	s_waitcnt vmcnt(15)
	v_mov_b32_e32 v72, v216
	v_mov_b32_e32 v73, v217
	v_mov_b32_e32 v74, v218
	v_mov_b32_e32 v75, v219
	v_lshlrev_b32_e32 v78, 16, v72
	v_and_b32_e32 v79, 0xffff0000, v72
	v_pk_mul_f32 v[64:65], v[64:65], v[76:77]
	v_lshlrev_b32_e32 v72, 16, v73
	v_pk_mul_f32 v[64:65], v[64:65], v[78:79]
	v_and_b32_e32 v73, 0xffff0000, v73
	v_cvt_pk_bf16_f32 v64, v64, v65
	v_mul_f32_e32 v65, 0xbfb8aa3b, v66
	v_exp_f32_e32 v65, v65
	s_nop 0
	v_add_f32_e32 v65, 1.0, v65
	v_rcp_f32_e32 v76, v65
	v_mul_f32_e32 v65, 0xbfb8aa3b, v67
	v_exp_f32_e32 v65, v65
	s_nop 0
	v_add_f32_e32 v65, 1.0, v65
	v_rcp_f32_e32 v77, v65
	s_nop 0
	v_pk_mul_f32 v[66:67], v[66:67], v[76:77]
	s_nop 0
	v_pk_mul_f32 v[66:67], v[66:67], v[72:73]
	v_lshlrev_b32_e32 v72, 16, v74
	v_cvt_pk_bf16_f32 v65, v66, v67
	v_mul_f32_e32 v66, 0xbfb8aa3b, v60
	v_mul_f32_e32 v67, 0xbfb8aa3b, v61
	v_exp_f32_e32 v66, v66
	v_exp_f32_e32 v67, v67
	v_and_b32_e32 v73, 0xffff0000, v74
	v_add_f32_e32 v66, 1.0, v66
	v_add_f32_e32 v67, 1.0, v67
	v_rcp_f32_e32 v66, v66
	v_rcp_f32_e32 v67, v67
	s_nop 0
	v_pk_mul_f32 v[60:61], v[60:61], v[66:67]
	s_nop 0
	v_pk_mul_f32 v[60:61], v[60:61], v[72:73]
	v_lshlrev_b32_e32 v72, 16, v75
	v_cvt_pk_bf16_f32 v66, v60, v61
	v_mul_f32_e32 v60, 0xbfb8aa3b, v62
	v_mul_f32_e32 v61, 0xbfb8aa3b, v63
	v_exp_f32_e32 v60, v60
	v_exp_f32_e32 v61, v61
	v_and_b32_e32 v73, 0xffff0000, v75
	v_add_f32_e32 v60, 1.0, v60
	v_add_f32_e32 v61, 1.0, v61
	v_rcp_f32_e32 v60, v60
	v_rcp_f32_e32 v61, v61
	s_nop 0
	v_pk_mul_f32 v[60:61], v[62:63], v[60:61]
	s_nop 0
	v_pk_mul_f32 v[60:61], v[60:61], v[72:73]
	s_nop 0
	v_cvt_pk_bf16_f32 v67, v60, v61
	v_lshl_add_u64 v[60:61], vcc, 0, v[70:71]
	global_store_dwordx4 v[68:69], v[64:67], off
	v_lshl_add_u64 v[60:61], v[60:61], 0, v[2:3]
	s_nop 1
	v_mul_f32_e32 v64, 0xbfb8aa3b, v56
	v_mul_f32_e32 v65, 0xbfb8aa3b, v57
	v_exp_f32_e32 v64, v64
	v_exp_f32_e32 v65, v65
	v_add_f32_e32 v64, 1.0, v64
	v_add_f32_e32 v65, 1.0, v65
	v_rcp_f32_e32 v64, v64
	v_rcp_f32_e32 v65, v65
	s_waitcnt vmcnt(15)
	v_mov_b32_e32 v60, v220
	v_mov_b32_e32 v61, v221
	v_mov_b32_e32 v62, v222
	v_mov_b32_e32 v63, v223
	v_lshlrev_b32_e32 v66, 16, v60
	v_and_b32_e32 v67, 0xffff0000, v60
	v_pk_mul_f32 v[56:57], v[56:57], v[64:65]
	v_lshlrev_b32_e32 v60, 16, v61
	v_pk_mul_f32 v[56:57], v[56:57], v[66:67]
	v_and_b32_e32 v61, 0xffff0000, v61
	v_cvt_pk_bf16_f32 v56, v56, v57
	v_mul_f32_e32 v57, 0xbfb8aa3b, v58
	v_exp_f32_e32 v57, v57
	s_nop 0
	v_add_f32_e32 v57, 1.0, v57
	v_rcp_f32_e32 v64, v57
	v_mul_f32_e32 v57, 0xbfb8aa3b, v59
	v_exp_f32_e32 v57, v57
	s_nop 0
	v_add_f32_e32 v57, 1.0, v57
	v_rcp_f32_e32 v65, v57
	s_nop 0
	v_pk_mul_f32 v[58:59], v[58:59], v[64:65]
	s_nop 0
	v_pk_mul_f32 v[58:59], v[58:59], v[60:61]
	v_lshlrev_b32_e32 v60, 16, v62
	v_cvt_pk_bf16_f32 v57, v58, v59
	v_mul_f32_e32 v58, 0xbfb8aa3b, v52
	v_mul_f32_e32 v59, 0xbfb8aa3b, v53
	v_exp_f32_e32 v58, v58
	v_exp_f32_e32 v59, v59
	v_and_b32_e32 v61, 0xffff0000, v62
	v_add_f32_e32 v58, 1.0, v58
	v_add_f32_e32 v59, 1.0, v59
	v_rcp_f32_e32 v58, v58
	v_rcp_f32_e32 v59, v59
	s_nop 0
	v_pk_mul_f32 v[52:53], v[52:53], v[58:59]
	s_nop 0
	v_pk_mul_f32 v[52:53], v[52:53], v[60:61]
	v_lshlrev_b32_e32 v60, 16, v63
	v_cvt_pk_bf16_f32 v58, v52, v53
	v_mul_f32_e32 v52, 0xbfb8aa3b, v54
	v_mul_f32_e32 v53, 0xbfb8aa3b, v55
	v_exp_f32_e32 v52, v52
	v_exp_f32_e32 v53, v53
	v_and_b32_e32 v61, 0xffff0000, v63
	v_add_f32_e32 v52, 1.0, v52
	v_add_f32_e32 v53, 1.0, v53
	v_rcp_f32_e32 v52, v52
	v_rcp_f32_e32 v53, v53
	s_nop 0
	v_pk_mul_f32 v[52:53], v[54:55], v[52:53]
	v_add_u32_e32 v54, 0x90, v150
	v_pk_mul_f32 v[52:53], v[52:53], v[60:61]
	v_ashrrev_i32_e32 v55, 31, v54
	v_cvt_pk_bf16_f32 v59, v52, v53
	v_lshlrev_b64 v[52:53], 11, v[54:55]
	v_lshlrev_b64 v[54:55], 7, v[54:55]
	global_store_dwordx4 v[68:69], v[56:59], off offset:256
	v_mul_f32_e32 v60, 0xbfb8aa3b, v48
	v_mul_f32_e32 v61, 0xbfb8aa3b, v49
	v_lshl_add_u64 v[56:57], s[54:55], 0, v[54:55]
	v_lshl_add_u64 v[56:57], v[56:57], 0, v[2:3]
	s_nop 1
	v_exp_f32_e32 v60, v60
	v_exp_f32_e32 v61, v61
	v_lshl_add_u64 v[52:53], s[2:3], 0, v[52:53]
	v_lshl_add_u64 v[52:53], v[52:53], 0, v[152:153]
	v_add_f32_e32 v60, 1.0, v60
	v_add_f32_e32 v61, 1.0, v61
	v_rcp_f32_e32 v60, v60
	v_rcp_f32_e32 v61, v61
	s_waitcnt vmcnt(15)
	v_mov_b32_e32 v56, v224
	v_mov_b32_e32 v57, v225
	v_mov_b32_e32 v58, v226
	v_mov_b32_e32 v59, v227
	v_lshlrev_b32_e32 v62, 16, v56
	v_and_b32_e32 v63, 0xffff0000, v56
	v_pk_mul_f32 v[48:49], v[48:49], v[60:61]
	v_lshlrev_b32_e32 v56, 16, v57
	v_pk_mul_f32 v[48:49], v[48:49], v[62:63]
	v_and_b32_e32 v57, 0xffff0000, v57
	v_cvt_pk_bf16_f32 v48, v48, v49
	v_mul_f32_e32 v49, 0xbfb8aa3b, v50
	v_exp_f32_e32 v49, v49
	s_nop 0
	v_add_f32_e32 v49, 1.0, v49
	v_rcp_f32_e32 v60, v49
	v_mul_f32_e32 v49, 0xbfb8aa3b, v51
	v_exp_f32_e32 v49, v49
	s_nop 0
	v_add_f32_e32 v49, 1.0, v49
	v_rcp_f32_e32 v61, v49
	s_nop 0
	v_pk_mul_f32 v[50:51], v[50:51], v[60:61]
	s_nop 0
	v_pk_mul_f32 v[50:51], v[50:51], v[56:57]
	v_lshlrev_b32_e32 v56, 16, v58
	v_cvt_pk_bf16_f32 v49, v50, v51
	v_mul_f32_e32 v50, 0xbfb8aa3b, v44
	v_mul_f32_e32 v51, 0xbfb8aa3b, v45
	v_exp_f32_e32 v50, v50
	v_exp_f32_e32 v51, v51
	v_and_b32_e32 v57, 0xffff0000, v58
	v_add_f32_e32 v50, 1.0, v50
	v_add_f32_e32 v51, 1.0, v51
	v_rcp_f32_e32 v50, v50
	v_rcp_f32_e32 v51, v51
	s_nop 0
	v_pk_mul_f32 v[44:45], v[44:45], v[50:51]
	s_nop 0
	v_pk_mul_f32 v[44:45], v[44:45], v[56:57]
	v_lshlrev_b32_e32 v56, 16, v59
	v_cvt_pk_bf16_f32 v50, v44, v45
	v_mul_f32_e32 v44, 0xbfb8aa3b, v46
	v_mul_f32_e32 v45, 0xbfb8aa3b, v47
	v_exp_f32_e32 v44, v44
	v_exp_f32_e32 v45, v45
	v_and_b32_e32 v57, 0xffff0000, v59
	v_add_f32_e32 v44, 1.0, v44
	v_add_f32_e32 v45, 1.0, v45
	v_rcp_f32_e32 v44, v44
	v_rcp_f32_e32 v45, v45
	s_nop 0
	v_pk_mul_f32 v[44:45], v[46:47], v[44:45]
	s_nop 0
	v_pk_mul_f32 v[44:45], v[44:45], v[56:57]
	s_nop 0
	v_cvt_pk_bf16_f32 v51, v44, v45
	v_lshl_add_u64 v[44:45], vcc, 0, v[54:55]
	global_store_dwordx4 v[52:53], v[48:51], off
	v_lshl_add_u64 v[44:45], v[44:45], 0, v[2:3]
	s_nop 1
	v_mul_f32_e32 v48, 0xbfb8aa3b, v40
	v_mul_f32_e32 v49, 0xbfb8aa3b, v41
	v_exp_f32_e32 v48, v48
	v_exp_f32_e32 v49, v49
	v_add_f32_e32 v48, 1.0, v48
	v_add_f32_e32 v49, 1.0, v49
	v_rcp_f32_e32 v48, v48
	v_rcp_f32_e32 v49, v49
	s_waitcnt vmcnt(15)
	v_mov_b32_e32 v44, v228
	v_mov_b32_e32 v45, v229
	v_mov_b32_e32 v46, v230
	v_mov_b32_e32 v47, v231
	v_lshlrev_b32_e32 v50, 16, v44
	v_and_b32_e32 v51, 0xffff0000, v44
	v_pk_mul_f32 v[40:41], v[40:41], v[48:49]
	v_lshlrev_b32_e32 v44, 16, v45
	v_pk_mul_f32 v[40:41], v[40:41], v[50:51]
	v_and_b32_e32 v45, 0xffff0000, v45
	v_cvt_pk_bf16_f32 v40, v40, v41
	v_mul_f32_e32 v41, 0xbfb8aa3b, v42
	v_exp_f32_e32 v41, v41
	s_nop 0
	v_add_f32_e32 v41, 1.0, v41
	v_rcp_f32_e32 v48, v41
	v_mul_f32_e32 v41, 0xbfb8aa3b, v43
	v_exp_f32_e32 v41, v41
	s_nop 0
	v_add_f32_e32 v41, 1.0, v41
	v_rcp_f32_e32 v49, v41
	s_nop 0
	v_pk_mul_f32 v[42:43], v[42:43], v[48:49]
	s_nop 0
	v_pk_mul_f32 v[42:43], v[42:43], v[44:45]
	v_lshlrev_b32_e32 v44, 16, v46
	v_cvt_pk_bf16_f32 v41, v42, v43
	v_mul_f32_e32 v42, 0xbfb8aa3b, v36
	v_mul_f32_e32 v43, 0xbfb8aa3b, v37
	v_exp_f32_e32 v42, v42
	v_exp_f32_e32 v43, v43
	v_and_b32_e32 v45, 0xffff0000, v46
	v_add_f32_e32 v42, 1.0, v42
	v_add_f32_e32 v43, 1.0, v43
	v_rcp_f32_e32 v42, v42
	v_rcp_f32_e32 v43, v43
	s_nop 0
	v_pk_mul_f32 v[36:37], v[36:37], v[42:43]
	s_nop 0
	v_pk_mul_f32 v[36:37], v[36:37], v[44:45]
	v_lshlrev_b32_e32 v44, 16, v47
	v_cvt_pk_bf16_f32 v42, v36, v37
	v_mul_f32_e32 v36, 0xbfb8aa3b, v38
	v_mul_f32_e32 v37, 0xbfb8aa3b, v39
	v_exp_f32_e32 v36, v36
	v_exp_f32_e32 v37, v37
	v_and_b32_e32 v45, 0xffff0000, v47
	v_add_f32_e32 v36, 1.0, v36
	v_add_f32_e32 v37, 1.0, v37
	v_rcp_f32_e32 v36, v36
	v_rcp_f32_e32 v37, v37
	s_nop 0
	v_pk_mul_f32 v[36:37], v[38:39], v[36:37]
	v_add_u32_e32 v38, 0xa0, v150
	v_pk_mul_f32 v[36:37], v[36:37], v[44:45]
	v_ashrrev_i32_e32 v39, 31, v38
	v_cvt_pk_bf16_f32 v43, v36, v37
	v_lshlrev_b64 v[36:37], 11, v[38:39]
	v_lshlrev_b64 v[38:39], 7, v[38:39]
	global_store_dwordx4 v[52:53], v[40:43], off offset:256
	v_mul_f32_e32 v44, 0xbfb8aa3b, v32
	v_mul_f32_e32 v45, 0xbfb8aa3b, v33
	v_lshl_add_u64 v[40:41], s[54:55], 0, v[38:39]
	v_lshl_add_u64 v[40:41], v[40:41], 0, v[2:3]
	s_nop 1
	v_exp_f32_e32 v44, v44
	v_exp_f32_e32 v45, v45
	v_lshl_add_u64 v[36:37], s[2:3], 0, v[36:37]
	v_lshl_add_u64 v[36:37], v[36:37], 0, v[152:153]
	v_add_f32_e32 v44, 1.0, v44
	v_add_f32_e32 v45, 1.0, v45
	v_rcp_f32_e32 v44, v44
	v_rcp_f32_e32 v45, v45
	s_waitcnt vmcnt(15)
	v_mov_b32_e32 v40, v232
	v_mov_b32_e32 v41, v233
	v_mov_b32_e32 v42, v234
	v_mov_b32_e32 v43, v235
	v_lshlrev_b32_e32 v46, 16, v40
	v_and_b32_e32 v47, 0xffff0000, v40
	v_pk_mul_f32 v[32:33], v[32:33], v[44:45]
	v_lshlrev_b32_e32 v40, 16, v41
	v_pk_mul_f32 v[32:33], v[32:33], v[46:47]
	v_and_b32_e32 v41, 0xffff0000, v41
	v_cvt_pk_bf16_f32 v32, v32, v33
	v_mul_f32_e32 v33, 0xbfb8aa3b, v34
	v_exp_f32_e32 v33, v33
	s_nop 0
	v_add_f32_e32 v33, 1.0, v33
	v_rcp_f32_e32 v44, v33
	v_mul_f32_e32 v33, 0xbfb8aa3b, v35
	v_exp_f32_e32 v33, v33
	s_nop 0
	v_add_f32_e32 v33, 1.0, v33
	v_rcp_f32_e32 v45, v33
	s_nop 0
	v_pk_mul_f32 v[34:35], v[34:35], v[44:45]
	s_nop 0
	v_pk_mul_f32 v[34:35], v[34:35], v[40:41]
	v_lshlrev_b32_e32 v40, 16, v42
	v_cvt_pk_bf16_f32 v33, v34, v35
	v_mul_f32_e32 v34, 0xbfb8aa3b, v28
	v_mul_f32_e32 v35, 0xbfb8aa3b, v29
	v_exp_f32_e32 v34, v34
	v_exp_f32_e32 v35, v35
	v_and_b32_e32 v41, 0xffff0000, v42
	v_add_f32_e32 v34, 1.0, v34
	v_add_f32_e32 v35, 1.0, v35
	v_rcp_f32_e32 v34, v34
	v_rcp_f32_e32 v35, v35
	s_nop 0
	v_pk_mul_f32 v[28:29], v[28:29], v[34:35]
	s_nop 0
	v_pk_mul_f32 v[28:29], v[28:29], v[40:41]
	v_lshlrev_b32_e32 v40, 16, v43
	v_cvt_pk_bf16_f32 v34, v28, v29
	v_mul_f32_e32 v28, 0xbfb8aa3b, v30
	v_mul_f32_e32 v29, 0xbfb8aa3b, v31
	v_exp_f32_e32 v28, v28
	v_exp_f32_e32 v29, v29
	v_and_b32_e32 v41, 0xffff0000, v43
	v_add_f32_e32 v28, 1.0, v28
	v_add_f32_e32 v29, 1.0, v29
	v_rcp_f32_e32 v28, v28
	v_rcp_f32_e32 v29, v29
	s_nop 0
	v_pk_mul_f32 v[28:29], v[30:31], v[28:29]
	s_nop 0
	v_pk_mul_f32 v[28:29], v[28:29], v[40:41]
	s_nop 0
	v_cvt_pk_bf16_f32 v35, v28, v29
	v_lshl_add_u64 v[28:29], vcc, 0, v[38:39]
	global_store_dwordx4 v[36:37], v[32:35], off
	v_lshl_add_u64 v[28:29], v[28:29], 0, v[2:3]
	s_nop 1
	v_mul_f32_e32 v32, 0xbfb8aa3b, v24
	v_mul_f32_e32 v33, 0xbfb8aa3b, v25
	v_exp_f32_e32 v32, v32
	v_exp_f32_e32 v33, v33
	v_add_f32_e32 v32, 1.0, v32
	v_add_f32_e32 v33, 1.0, v33
	v_rcp_f32_e32 v32, v32
	v_rcp_f32_e32 v33, v33
	s_waitcnt vmcnt(15)
	v_mov_b32_e32 v28, v236
	v_mov_b32_e32 v29, v237
	v_mov_b32_e32 v30, v238
	v_mov_b32_e32 v31, v239
	v_lshlrev_b32_e32 v34, 16, v28
	v_and_b32_e32 v35, 0xffff0000, v28
	v_pk_mul_f32 v[24:25], v[24:25], v[32:33]
	v_lshlrev_b32_e32 v28, 16, v29
	v_pk_mul_f32 v[24:25], v[24:25], v[34:35]
	v_and_b32_e32 v29, 0xffff0000, v29
	v_cvt_pk_bf16_f32 v24, v24, v25
	v_mul_f32_e32 v25, 0xbfb8aa3b, v26
	v_exp_f32_e32 v25, v25
	s_nop 0
	v_add_f32_e32 v25, 1.0, v25
	v_rcp_f32_e32 v32, v25
	v_mul_f32_e32 v25, 0xbfb8aa3b, v27
	v_exp_f32_e32 v25, v25
	s_nop 0
	v_add_f32_e32 v25, 1.0, v25
	v_rcp_f32_e32 v33, v25
	s_nop 0
	v_pk_mul_f32 v[26:27], v[26:27], v[32:33]
	s_nop 0
	v_pk_mul_f32 v[26:27], v[26:27], v[28:29]
	v_lshlrev_b32_e32 v28, 16, v30
	v_cvt_pk_bf16_f32 v25, v26, v27
	v_mul_f32_e32 v26, 0xbfb8aa3b, v20
	v_mul_f32_e32 v27, 0xbfb8aa3b, v21
	v_exp_f32_e32 v26, v26
	v_exp_f32_e32 v27, v27
	v_and_b32_e32 v29, 0xffff0000, v30
	v_add_f32_e32 v26, 1.0, v26
	v_add_f32_e32 v27, 1.0, v27
	v_rcp_f32_e32 v26, v26
	v_rcp_f32_e32 v27, v27
	s_nop 0
	v_pk_mul_f32 v[20:21], v[20:21], v[26:27]
	s_nop 0
	v_pk_mul_f32 v[20:21], v[20:21], v[28:29]
	v_lshlrev_b32_e32 v28, 16, v31
	v_cvt_pk_bf16_f32 v26, v20, v21
	v_mul_f32_e32 v20, 0xbfb8aa3b, v22
	v_mul_f32_e32 v21, 0xbfb8aa3b, v23
	v_exp_f32_e32 v20, v20
	v_exp_f32_e32 v21, v21
	v_and_b32_e32 v29, 0xffff0000, v31
	v_add_f32_e32 v20, 1.0, v20
	v_add_f32_e32 v21, 1.0, v21
	v_rcp_f32_e32 v20, v20
	v_rcp_f32_e32 v21, v21
	s_nop 0
	v_pk_mul_f32 v[20:21], v[22:23], v[20:21]
	v_add_u32_e32 v22, 0xb0, v150
	v_pk_mul_f32 v[20:21], v[20:21], v[28:29]
	v_ashrrev_i32_e32 v23, 31, v22
	v_cvt_pk_bf16_f32 v27, v20, v21
	v_lshlrev_b64 v[20:21], 11, v[22:23]
	v_lshlrev_b64 v[22:23], 7, v[22:23]
	global_store_dwordx4 v[36:37], v[24:27], off offset:256
	v_mul_f32_e32 v28, 0xbfb8aa3b, v16
	v_mul_f32_e32 v29, 0xbfb8aa3b, v17
	v_lshl_add_u64 v[24:25], s[54:55], 0, v[22:23]
	v_lshl_add_u64 v[24:25], v[24:25], 0, v[2:3]
	s_nop 1
	v_exp_f32_e32 v28, v28
	v_exp_f32_e32 v29, v29
	v_lshl_add_u64 v[20:21], s[2:3], 0, v[20:21]
	v_lshl_add_u64 v[20:21], v[20:21], 0, v[152:153]
	v_add_f32_e32 v28, 1.0, v28
	v_add_f32_e32 v29, 1.0, v29
	v_rcp_f32_e32 v28, v28
	v_rcp_f32_e32 v29, v29
	s_mov_b64 s[54:55], -1
	v_pk_mul_f32 v[16:17], v[16:17], v[28:29]
	s_waitcnt vmcnt(15)
	v_mov_b32_e32 v24, v240
	v_mov_b32_e32 v25, v241
	v_mov_b32_e32 v26, v242
	v_mov_b32_e32 v27, v243
	v_lshlrev_b32_e32 v30, 16, v24
	v_and_b32_e32 v31, 0xffff0000, v24
	v_pk_mul_f32 v[16:17], v[16:17], v[30:31]
	v_lshlrev_b32_e32 v24, 16, v25
	v_cvt_pk_bf16_f32 v16, v16, v17
	v_mul_f32_e32 v17, 0xbfb8aa3b, v18
	v_exp_f32_e32 v17, v17
	v_and_b32_e32 v25, 0xffff0000, v25
	v_add_f32_e32 v17, 1.0, v17
	v_rcp_f32_e32 v28, v17
	v_mul_f32_e32 v17, 0xbfb8aa3b, v19
	v_exp_f32_e32 v17, v17
	s_nop 0
	v_add_f32_e32 v17, 1.0, v17
	v_rcp_f32_e32 v29, v17
	s_nop 0
	v_pk_mul_f32 v[18:19], v[18:19], v[28:29]
	s_nop 0
	v_pk_mul_f32 v[18:19], v[18:19], v[24:25]
	v_lshlrev_b32_e32 v24, 16, v26
	v_cvt_pk_bf16_f32 v17, v18, v19
	v_mul_f32_e32 v18, 0xbfb8aa3b, v12
	v_mul_f32_e32 v19, 0xbfb8aa3b, v13
	v_exp_f32_e32 v18, v18
	v_exp_f32_e32 v19, v19
	v_and_b32_e32 v25, 0xffff0000, v26
	v_add_f32_e32 v18, 1.0, v18
	v_add_f32_e32 v19, 1.0, v19
	v_rcp_f32_e32 v18, v18
	v_rcp_f32_e32 v19, v19
	s_nop 0
	v_pk_mul_f32 v[12:13], v[12:13], v[18:19]
	s_nop 0
	v_pk_mul_f32 v[12:13], v[12:13], v[24:25]
	v_lshlrev_b32_e32 v24, 16, v27
	v_cvt_pk_bf16_f32 v18, v12, v13
	v_mul_f32_e32 v12, 0xbfb8aa3b, v14
	v_mul_f32_e32 v13, 0xbfb8aa3b, v15
	v_exp_f32_e32 v12, v12
	v_exp_f32_e32 v13, v13
	v_and_b32_e32 v25, 0xffff0000, v27
	v_add_f32_e32 v12, 1.0, v12
	v_add_f32_e32 v13, 1.0, v13
	v_rcp_f32_e32 v12, v12
	v_rcp_f32_e32 v13, v13
	s_nop 0
	v_pk_mul_f32 v[12:13], v[14:15], v[12:13]
	s_nop 0
	v_pk_mul_f32 v[12:13], v[12:13], v[24:25]
	s_nop 0
	v_cvt_pk_bf16_f32 v19, v12, v13
	v_lshl_add_u64 v[12:13], vcc, 0, v[22:23]
	global_store_dwordx4 v[20:21], v[16:19], off
	v_lshl_add_u64 v[12:13], v[12:13], 0, v[2:3]
	s_nop 1
	v_mul_f32_e32 v2, 0xbfb8aa3b, v8
	v_exp_f32_e32 v2, v2
	s_andn2_b64 vcc, exec, s[4:5]
	v_add_f32_e32 v2, 1.0, v2
	v_rcp_f32_e32 v16, v2
	v_mul_f32_e32 v2, 0xbfb8aa3b, v9
	v_exp_f32_e32 v2, v2
	s_waitcnt vmcnt(15)
	v_mov_b32_e32 v12, v244
	v_mov_b32_e32 v13, v245
	v_mov_b32_e32 v14, v246
	v_mov_b32_e32 v15, v247
	v_lshlrev_b32_e32 v18, 16, v12
	v_add_f32_e32 v2, 1.0, v2
	v_rcp_f32_e32 v17, v2
	v_mul_f32_e32 v2, 0xbfb8aa3b, v10
	v_exp_f32_e32 v2, v2
	v_and_b32_e32 v19, 0xffff0000, v12
	v_pk_mul_f32 v[8:9], v[8:9], v[16:17]
	v_lshlrev_b32_e32 v12, 16, v13
	v_add_f32_e32 v2, 1.0, v2
	v_rcp_f32_e32 v16, v2
	v_mul_f32_e32 v2, 0xbfb8aa3b, v11
	v_exp_f32_e32 v2, v2
	v_and_b32_e32 v13, 0xffff0000, v13
	v_pk_mul_f32 v[8:9], v[8:9], v[18:19]
	v_add_f32_e32 v2, 1.0, v2
	v_rcp_f32_e32 v17, v2
	v_mul_f32_e32 v2, 0xbfb8aa3b, v4
	v_exp_f32_e32 v2, v2
	v_cvt_pk_bf16_f32 v8, v8, v9
	v_pk_mul_f32 v[10:11], v[10:11], v[16:17]
	v_add_f32_e32 v2, 1.0, v2
	v_pk_mul_f32 v[10:11], v[10:11], v[12:13]
	v_lshlrev_b32_e32 v12, 16, v14
	v_cvt_pk_bf16_f32 v9, v10, v11
	v_rcp_f32_e32 v10, v2
	v_mul_f32_e32 v2, 0xbfb8aa3b, v5
	v_exp_f32_e32 v2, v2
	v_and_b32_e32 v13, 0xffff0000, v14
	v_add_f32_e32 v2, 1.0, v2
	v_rcp_f32_e32 v11, v2
	v_mul_f32_e32 v2, 0xbfb8aa3b, v6
	v_exp_f32_e32 v2, v2
	v_pk_mul_f32 v[4:5], v[4:5], v[10:11]
	s_nop 0
	v_pk_mul_f32 v[4:5], v[4:5], v[12:13]
	v_add_f32_e32 v2, 1.0, v2
	v_cvt_pk_bf16_f32 v10, v4, v5
	v_rcp_f32_e32 v4, v2
	v_mul_f32_e32 v2, 0xbfb8aa3b, v7
	v_exp_f32_e32 v2, v2
	v_lshlrev_b32_e32 v12, 16, v15
	v_and_b32_e32 v13, 0xffff0000, v15
	v_add_f32_e32 v2, 1.0, v2
	v_rcp_f32_e32 v5, v2
	s_nop 0
	v_pk_mul_f32 v[4:5], v[6:7], v[4:5]
	s_nop 0
	v_pk_mul_f32 v[4:5], v[4:5], v[12:13]
	s_nop 0
	v_cvt_pk_bf16_f32 v11, v4, v5
	global_store_dwordx4 v[20:21], v[8:11], off offset:256
	s_cbranch_vccnz .LBB0_1066
	s_andn2_b64 vcc, exec, s[18:19]
	s_cbranch_vccnz .LBB0_1065
	s_barrier
	s_branch .LBB0_1065
